# out-proj->up and up->down seams: barrier among the 4 workgroups owning the same token tile; out-proj's row-sum atomics made returning so vmcnt(0) before the barrier means they were performed
# speedup vs baseline: 1.0154x; 1.0108x over previous
.LBB0_568:
	s_add_u32 s36, s28, 0xfffc0080
	s_addc_u32 s37, s29, -1
	s_add_i32 s68, s44, 0x120
	s_cmp_eq_u32 s67, 12
	s_cselect_b32 s39, s23, s37
	s_cselect_b32 s38, s61, s36
	v_add_u32_e32 v142, s68, v145
	s_cselect_b32 s37, s21, s66
	s_cselect_b32 s36, s62, s63
	s_add_i32 s70, s45, 0x120
	ds_read_b128 v[138:141], v142
	ds_read_b128 v[148:151], v142 offset:1024
	ds_read_b128 v[152:155], v142 offset:2048
	ds_read_b128 v[156:159], v142 offset:3072
	v_add_u32_e32 v142, s70, v145
	ds_read_b128 v[200:203], v142
	ds_read_b128 v[204:207], v142 offset:1024
	ds_read_b128 v[208:211], v142 offset:2048
	ds_read_b128 v[212:215], v142 offset:3072
	v_lshl_add_u64 v[142:143], s[28:29], 0, v[134:135]
	s_add_i32 m0, s52, 0xc000
	ds_read_b128 v[216:219], v147
	ds_read_b128 v[220:223], v147 offset:1024
	ds_read_b128 v[224:227], v147 offset:2048
	ds_read_b128 v[228:231], v147 offset:3072
	ds_read_b128 v[232:235], v147 offset:4096
	ds_read_b128 v[236:239], v147 offset:5120
	ds_read_b128 v[240:243], v147 offset:6144
	ds_read_b128 v[244:247], v147 offset:7168
	global_load_lds_dwordx4 v[142:143], off
	v_lshl_add_u64 v[142:143], s[28:29], 0, v[136:137]
	s_add_i32 m0, s52, 0xe000
	s_nop 0
	global_load_lds_dwordx4 v[142:143], off
	s_waitcnt vmcnt(8)
	s_waitcnt lgkmcnt(0)
	s_barrier
	s_setprio 1
	s_waitcnt lgkmcnt(0)
	v_mfma_f32_16x16x32_bf16 v[124:127], v[138:141], v[216:219], v[124:127]
	v_mfma_f32_16x16x32_bf16 v[120:123], v[152:155], v[216:219], v[120:123]
	v_mfma_f32_16x16x32_bf16 v[108:111], v[138:141], v[224:227], v[108:111]
	v_mfma_f32_16x16x32_bf16 v[104:107], v[152:155], v[224:227], v[104:107]
	v_mfma_f32_16x16x32_bf16 v[92:95], v[138:141], v[232:235], v[92:95]
	v_mfma_f32_16x16x32_bf16 v[88:91], v[152:155], v[232:235], v[88:91]
	v_mfma_f32_16x16x32_bf16 v[76:79], v[138:141], v[240:243], v[76:79]
	v_mfma_f32_16x16x32_bf16 v[72:75], v[152:155], v[240:243], v[72:75]
	v_mfma_f32_16x16x32_bf16 v[124:127], v[148:151], v[220:223], v[124:127]
	v_mfma_f32_16x16x32_bf16 v[120:123], v[156:159], v[220:223], v[120:123]
	v_mfma_f32_16x16x32_bf16 v[108:111], v[148:151], v[228:231], v[108:111]
	v_mfma_f32_16x16x32_bf16 v[104:107], v[156:159], v[228:231], v[104:107]
	v_mfma_f32_16x16x32_bf16 v[92:95], v[148:151], v[236:239], v[92:95]
	v_mfma_f32_16x16x32_bf16 v[88:91], v[156:159], v[236:239], v[88:91]
	v_mfma_f32_16x16x32_bf16 v[76:79], v[148:151], v[244:247], v[76:79]
	v_mfma_f32_16x16x32_bf16 v[72:75], v[156:159], v[244:247], v[72:75]
	s_setprio 0
	s_setprio 1
	v_mfma_f32_16x16x32_bf16 v[116:119], v[200:203], v[216:219], v[116:119]
	v_mfma_f32_16x16x32_bf16 v[112:115], v[208:211], v[216:219], v[112:115]
	v_mfma_f32_16x16x32_bf16 v[100:103], v[200:203], v[224:227], v[100:103]
	v_mfma_f32_16x16x32_bf16 v[96:99], v[208:211], v[224:227], v[96:99]
	v_mfma_f32_16x16x32_bf16 v[84:87], v[200:203], v[232:235], v[84:87]
	v_mfma_f32_16x16x32_bf16 v[80:83], v[208:211], v[232:235], v[80:83]
	v_mfma_f32_16x16x32_bf16 v[68:71], v[200:203], v[240:243], v[68:71]
	v_mfma_f32_16x16x32_bf16 v[64:67], v[208:211], v[240:243], v[64:67]
	v_mfma_f32_16x16x32_bf16 v[116:119], v[204:207], v[220:223], v[116:119]
	v_mfma_f32_16x16x32_bf16 v[112:115], v[212:215], v[220:223], v[112:115]
	v_mfma_f32_16x16x32_bf16 v[100:103], v[204:207], v[228:231], v[100:103]
	v_mfma_f32_16x16x32_bf16 v[96:99], v[212:215], v[228:231], v[96:99]
	v_mfma_f32_16x16x32_bf16 v[84:87], v[204:207], v[236:239], v[84:87]
	v_mfma_f32_16x16x32_bf16 v[80:83], v[212:215], v[236:239], v[80:83]
	v_mfma_f32_16x16x32_bf16 v[68:71], v[204:207], v[244:247], v[68:71]
	v_mfma_f32_16x16x32_bf16 v[64:67], v[212:215], v[244:247], v[64:67]
	s_setprio 0
	s_barrier
	s_add_i32 s68, s68, s49
	v_lshl_add_u64 v[142:143], s[36:37], 0, v[160:161]
	s_mov_b32 m0, s68
	ds_read_b128 v[216:219], v147 offset:16384
	ds_read_b128 v[220:223], v147 offset:17408
	ds_read_b128 v[224:227], v147 offset:18432
	ds_read_b128 v[228:231], v147 offset:19456
	ds_read_b128 v[232:235], v147 offset:20480
	ds_read_b128 v[236:239], v147 offset:21504
	ds_read_b128 v[240:243], v147 offset:22528
	ds_read_b128 v[244:247], v147 offset:23552
	global_load_lds_dwordx4 v[142:143], off
	s_add_i32 m0, s68, 0x2000
	s_add_u32 s68, s36, 0x40000
	v_lshl_add_u64 v[170:171], s[36:37], 0, v[128:129]
	s_addc_u32 s69, s37, 0
	s_add_i32 s70, s70, s49
	global_load_lds_dwordx4 v[170:171], off
	v_lshl_add_u64 v[174:175], s[68:69], 0, v[160:161]
	s_mov_b32 m0, s70
	v_lshl_add_u64 v[198:199], s[38:39], 0, v[130:131]
	global_load_lds_dwordx4 v[174:175], off
	v_lshl_add_u64 v[174:175], s[68:69], 0, v[128:129]
	s_add_i32 m0, s70, 0x2000
	s_nop 0
	global_load_lds_dwordx4 v[174:175], off
	v_lshl_add_u64 v[174:175], s[38:39], 0, v[132:133]
	s_mov_b32 m0, s52
	s_nop 0
	global_load_lds_dwordx4 v[174:175], off
	s_mov_b32 m0, s53
	s_nop 0
	global_load_lds_dwordx4 v[198:199], off
	s_waitcnt vmcnt(8)
	s_waitcnt lgkmcnt(0)
	s_barrier
	s_setprio 1
	s_waitcnt lgkmcnt(0)
	v_mfma_f32_16x16x32_bf16 v[60:63], v[138:141], v[216:219], v[60:63]
	v_mfma_f32_16x16x32_bf16 v[56:59], v[152:155], v[216:219], v[56:59]
	v_mfma_f32_16x16x32_bf16 v[44:47], v[138:141], v[224:227], v[44:47]
	v_mfma_f32_16x16x32_bf16 v[40:43], v[152:155], v[224:227], v[40:43]
	v_mfma_f32_16x16x32_bf16 v[28:31], v[138:141], v[232:235], v[28:31]
	v_mfma_f32_16x16x32_bf16 v[24:27], v[152:155], v[232:235], v[24:27]
	v_mfma_f32_16x16x32_bf16 v[12:15], v[138:141], v[240:243], v[12:15]
	v_mfma_f32_16x16x32_bf16 v[8:11], v[152:155], v[240:243], v[8:11]
	v_mfma_f32_16x16x32_bf16 v[60:63], v[148:151], v[220:223], v[60:63]
	v_mfma_f32_16x16x32_bf16 v[56:59], v[156:159], v[220:223], v[56:59]
	v_mfma_f32_16x16x32_bf16 v[44:47], v[148:151], v[228:231], v[44:47]
	v_mfma_f32_16x16x32_bf16 v[40:43], v[156:159], v[228:231], v[40:43]
	v_mfma_f32_16x16x32_bf16 v[28:31], v[148:151], v[236:239], v[28:31]
	v_mfma_f32_16x16x32_bf16 v[24:27], v[156:159], v[236:239], v[24:27]
	v_mfma_f32_16x16x32_bf16 v[12:15], v[148:151], v[244:247], v[12:15]
	v_mfma_f32_16x16x32_bf16 v[8:11], v[156:159], v[244:247], v[8:11]
	s_setprio 0
	s_setprio 1
	v_mfma_f32_16x16x32_bf16 v[52:55], v[200:203], v[216:219], v[52:55]
	v_mfma_f32_16x16x32_bf16 v[48:51], v[208:211], v[216:219], v[48:51]
	v_mfma_f32_16x16x32_bf16 v[36:39], v[200:203], v[224:227], v[36:39]
	v_mfma_f32_16x16x32_bf16 v[32:35], v[208:211], v[224:227], v[32:35]
	v_mfma_f32_16x16x32_bf16 v[20:23], v[200:203], v[232:235], v[20:23]
	v_mfma_f32_16x16x32_bf16 v[16:19], v[208:211], v[232:235], v[16:19]
	v_mfma_f32_16x16x32_bf16 v[4:7], v[200:203], v[240:243], v[4:7]
	v_mfma_f32_16x16x32_bf16 v[0:3], v[208:211], v[240:243], v[0:3]
	v_mfma_f32_16x16x32_bf16 v[52:55], v[204:207], v[220:223], v[52:55]
	v_mfma_f32_16x16x32_bf16 v[48:51], v[212:215], v[220:223], v[48:51]
	v_mfma_f32_16x16x32_bf16 v[36:39], v[204:207], v[228:231], v[36:39]
	v_mfma_f32_16x16x32_bf16 v[32:35], v[212:215], v[228:231], v[32:35]
	v_mfma_f32_16x16x32_bf16 v[20:23], v[204:207], v[236:239], v[20:23]
	v_mfma_f32_16x16x32_bf16 v[16:19], v[212:215], v[236:239], v[16:19]
	v_mfma_f32_16x16x32_bf16 v[4:7], v[204:207], v[244:247], v[4:7]
	v_mfma_f32_16x16x32_bf16 v[0:3], v[212:215], v[244:247], v[0:3]
	s_setprio 0
	s_barrier
	s_add_i32 s68, s46, 0x120
	s_add_i32 s69, s47, 0x120
	v_add_u32_e32 v156, s68, v145
	v_add_u32_e32 v172, s69, v145
	ds_read_b128 v[138:141], v156
	ds_read_b128 v[148:151], v156 offset:1024
	ds_read_b128 v[152:155], v156 offset:2048
	ds_read_b128 v[156:159], v156 offset:3072
	ds_read_b128 v[200:203], v172
	ds_read_b128 v[204:207], v172 offset:1024
	ds_read_b128 v[208:211], v172 offset:2048
	ds_read_b128 v[212:215], v172 offset:3072
	s_add_u32 s38, s38, 0x40000
	s_addc_u32 s39, s39, 0
	s_mov_b32 m0, s56
	v_lshl_add_u64 v[248:249], s[38:39], 0, v[132:133]
	ds_read_b128 v[216:219], v147 offset:32768
	ds_read_b128 v[220:223], v147 offset:33792
	ds_read_b128 v[224:227], v147 offset:34816
	ds_read_b128 v[228:231], v147 offset:35840
	ds_read_b128 v[232:235], v147 offset:36864
	ds_read_b128 v[236:239], v147 offset:37888
	ds_read_b128 v[240:243], v147 offset:38912
	ds_read_b128 v[244:247], v147 offset:39936
	global_load_lds_dwordx4 v[248:249], off
	v_lshl_add_u64 v[248:249], s[38:39], 0, v[130:131]
	s_mov_b32 m0, s57
	s_nop 0
	global_load_lds_dwordx4 v[248:249], off
	s_waitcnt vmcnt(8)
	s_waitcnt lgkmcnt(0)
	s_barrier
	s_setprio 1
	s_waitcnt lgkmcnt(0)
	v_mfma_f32_16x16x32_bf16 v[124:127], v[138:141], v[216:219], v[124:127]
	v_mfma_f32_16x16x32_bf16 v[120:123], v[152:155], v[216:219], v[120:123]
	v_mfma_f32_16x16x32_bf16 v[108:111], v[138:141], v[224:227], v[108:111]
	v_mfma_f32_16x16x32_bf16 v[104:107], v[152:155], v[224:227], v[104:107]
	v_mfma_f32_16x16x32_bf16 v[92:95], v[138:141], v[232:235], v[92:95]
	v_mfma_f32_16x16x32_bf16 v[88:91], v[152:155], v[232:235], v[88:91]
	v_mfma_f32_16x16x32_bf16 v[76:79], v[138:141], v[240:243], v[76:79]
	v_mfma_f32_16x16x32_bf16 v[72:75], v[152:155], v[240:243], v[72:75]
	v_mfma_f32_16x16x32_bf16 v[124:127], v[148:151], v[220:223], v[124:127]
	v_mfma_f32_16x16x32_bf16 v[120:123], v[156:159], v[220:223], v[120:123]
	v_mfma_f32_16x16x32_bf16 v[108:111], v[148:151], v[228:231], v[108:111]
	v_mfma_f32_16x16x32_bf16 v[104:107], v[156:159], v[228:231], v[104:107]
	v_mfma_f32_16x16x32_bf16 v[92:95], v[148:151], v[236:239], v[92:95]
	v_mfma_f32_16x16x32_bf16 v[88:91], v[156:159], v[236:239], v[88:91]
	v_mfma_f32_16x16x32_bf16 v[76:79], v[148:151], v[244:247], v[76:79]
	v_mfma_f32_16x16x32_bf16 v[72:75], v[156:159], v[244:247], v[72:75]
	s_setprio 0
	s_setprio 1
	v_mfma_f32_16x16x32_bf16 v[116:119], v[200:203], v[216:219], v[116:119]
	v_mfma_f32_16x16x32_bf16 v[112:115], v[208:211], v[216:219], v[112:115]
	v_mfma_f32_16x16x32_bf16 v[100:103], v[200:203], v[224:227], v[100:103]
	v_mfma_f32_16x16x32_bf16 v[96:99], v[208:211], v[224:227], v[96:99]
	v_mfma_f32_16x16x32_bf16 v[84:87], v[200:203], v[232:235], v[84:87]
	v_mfma_f32_16x16x32_bf16 v[80:83], v[208:211], v[232:235], v[80:83]
	v_mfma_f32_16x16x32_bf16 v[68:71], v[200:203], v[240:243], v[68:71]
	v_mfma_f32_16x16x32_bf16 v[64:67], v[208:211], v[240:243], v[64:67]
	v_mfma_f32_16x16x32_bf16 v[116:119], v[204:207], v[220:223], v[116:119]
	v_mfma_f32_16x16x32_bf16 v[112:115], v[212:215], v[220:223], v[112:115]
	v_mfma_f32_16x16x32_bf16 v[100:103], v[204:207], v[228:231], v[100:103]
	v_mfma_f32_16x16x32_bf16 v[96:99], v[212:215], v[228:231], v[96:99]
	v_mfma_f32_16x16x32_bf16 v[84:87], v[204:207], v[236:239], v[84:87]
	v_mfma_f32_16x16x32_bf16 v[80:83], v[212:215], v[236:239], v[80:83]
	v_mfma_f32_16x16x32_bf16 v[68:71], v[204:207], v[244:247], v[68:71]
	v_mfma_f32_16x16x32_bf16 v[64:67], v[212:215], v[244:247], v[64:67]
	s_setprio 0
	s_barrier
	s_add_i32 s38, s68, s49
	v_lshl_add_u64 v[142:143], v[142:143], 0, s[88:89]
	s_mov_b32 m0, s38
	ds_read_b128 v[216:219], v147 offset:49152
	ds_read_b128 v[220:223], v147 offset:50176
	ds_read_b128 v[224:227], v147 offset:51200
	ds_read_b128 v[228:231], v147 offset:52224
	ds_read_b128 v[232:235], v147 offset:53248
	ds_read_b128 v[236:239], v147 offset:54272
	ds_read_b128 v[240:243], v147 offset:55296
	ds_read_b128 v[244:247], v147 offset:56320
	global_load_lds_dwordx4 v[142:143], off
	s_add_i32 m0, s38, 0x2000
	s_add_u32 s36, s36, 0x40080
	v_lshl_add_u64 v[142:143], v[170:171], 0, s[88:89]
	s_addc_u32 s37, s37, 0
	s_add_i32 s38, s69, s49
	global_load_lds_dwordx4 v[142:143], off
	v_lshl_add_u64 v[142:143], s[36:37], 0, v[160:161]
	s_mov_b32 m0, s38
	s_nop 0
	global_load_lds_dwordx4 v[142:143], off
	v_lshl_add_u64 v[142:143], s[36:37], 0, v[128:129]
	s_add_i32 m0, s38, 0x2000
	s_nop 0
	global_load_lds_dwordx4 v[142:143], off
	v_lshl_add_u64 v[142:143], v[174:175], 0, s[88:89]
	s_mov_b32 m0, s58
	s_nop 0
	global_load_lds_dwordx4 v[142:143], off
	v_lshl_add_u64 v[142:143], v[198:199], 0, s[88:89]
	s_mov_b32 m0, s59
	s_nop 0
	global_load_lds_dwordx4 v[142:143], off
	s_waitcnt vmcnt(8)
	s_waitcnt lgkmcnt(0)
	s_barrier
	s_setprio 1
	s_waitcnt lgkmcnt(0)
	v_mfma_f32_16x16x32_bf16 v[60:63], v[138:141], v[216:219], v[60:63]
	v_mfma_f32_16x16x32_bf16 v[56:59], v[152:155], v[216:219], v[56:59]
	v_mfma_f32_16x16x32_bf16 v[44:47], v[138:141], v[224:227], v[44:47]
	v_mfma_f32_16x16x32_bf16 v[40:43], v[152:155], v[224:227], v[40:43]
	v_mfma_f32_16x16x32_bf16 v[28:31], v[138:141], v[232:235], v[28:31]
	v_mfma_f32_16x16x32_bf16 v[24:27], v[152:155], v[232:235], v[24:27]
	v_mfma_f32_16x16x32_bf16 v[12:15], v[138:141], v[240:243], v[12:15]
	v_mfma_f32_16x16x32_bf16 v[8:11], v[152:155], v[240:243], v[8:11]
	v_mfma_f32_16x16x32_bf16 v[60:63], v[148:151], v[220:223], v[60:63]
	v_mfma_f32_16x16x32_bf16 v[56:59], v[156:159], v[220:223], v[56:59]
	v_mfma_f32_16x16x32_bf16 v[44:47], v[148:151], v[228:231], v[44:47]
	v_mfma_f32_16x16x32_bf16 v[40:43], v[156:159], v[228:231], v[40:43]
	v_mfma_f32_16x16x32_bf16 v[28:31], v[148:151], v[236:239], v[28:31]
	v_mfma_f32_16x16x32_bf16 v[24:27], v[156:159], v[236:239], v[24:27]
	v_mfma_f32_16x16x32_bf16 v[12:15], v[148:151], v[244:247], v[12:15]
	v_mfma_f32_16x16x32_bf16 v[8:11], v[156:159], v[244:247], v[8:11]
	s_setprio 0
	s_setprio 1
	v_mfma_f32_16x16x32_bf16 v[52:55], v[200:203], v[216:219], v[52:55]
	v_mfma_f32_16x16x32_bf16 v[48:51], v[208:211], v[216:219], v[48:51]
	v_mfma_f32_16x16x32_bf16 v[36:39], v[200:203], v[224:227], v[36:39]
	v_mfma_f32_16x16x32_bf16 v[32:35], v[208:211], v[224:227], v[32:35]
	v_mfma_f32_16x16x32_bf16 v[20:23], v[200:203], v[232:235], v[20:23]
	v_mfma_f32_16x16x32_bf16 v[16:19], v[208:211], v[232:235], v[16:19]
	v_mfma_f32_16x16x32_bf16 v[4:7], v[200:203], v[240:243], v[4:7]
	v_mfma_f32_16x16x32_bf16 v[0:3], v[208:211], v[240:243], v[0:3]
	v_mfma_f32_16x16x32_bf16 v[52:55], v[204:207], v[220:223], v[52:55]
	v_mfma_f32_16x16x32_bf16 v[48:51], v[212:215], v[220:223], v[48:51]
	v_mfma_f32_16x16x32_bf16 v[36:39], v[204:207], v[228:231], v[36:39]
	v_mfma_f32_16x16x32_bf16 v[32:35], v[212:215], v[228:231], v[32:35]
	v_mfma_f32_16x16x32_bf16 v[20:23], v[204:207], v[236:239], v[20:23]
	v_mfma_f32_16x16x32_bf16 v[16:19], v[212:215], v[236:239], v[16:19]
	v_mfma_f32_16x16x32_bf16 v[4:7], v[204:207], v[244:247], v[4:7]
	v_mfma_f32_16x16x32_bf16 v[0:3], v[212:215], v[244:247], v[0:3]
	s_setprio 0
	s_barrier
	s_add_i32 s67, s67, 2
	s_add_u32 s28, s28, 0x100
	s_addc_u32 s29, s29, 0
	s_add_u32 s63, s63, 0x100
	s_addc_u32 s66, s66, 0
	s_cmp_gt_u32 s67, 13
	s_cbranch_scc0 .LBB0_568
	v_lshl_add_u32 v142, s51, 8, v144
	v_lshl_or_b32 v140, s1, 8, v146
	v_ashrrev_i32_e32 v143, 31, v142
	v_ashrrev_i32_e32 v141, 31, v140
	v_lshlrev_b64 v[138:139], 10, v[142:143]
	v_lshl_add_u64 v[138:139], v[138:139], 0, v[140:141]
	v_lshlrev_b64 v[156:157], 2, v[138:139]
	v_lshl_add_u64 v[158:159], s[16:17], 0, v[156:157]
	v_mov_b32_e32 v248, v158
	v_mov_b32_e32 v249, v159
	global_load_dwordx4 v[200:203], v[248:249], off
	global_load_dwordx4 v[204:207], v[248:249], off offset:16
	global_load_dwordx4 v[208:211], v[248:249], off offset:512
	global_load_dwordx4 v[212:215], v[248:249], off offset:528
	s_mov_b64 s[98:99], 0x10000
	v_lshl_add_u64 v[250:251], v[248:249], 0, s[98:99]
	global_load_dwordx4 v[216:219], v[250:251], off
	global_load_dwordx4 v[220:223], v[250:251], off offset:16
	global_load_dwordx4 v[224:227], v[250:251], off offset:512
	global_load_dwordx4 v[228:231], v[250:251], off offset:528
	s_mov_b64 s[98:99], 0x20000
	v_lshl_add_u64 v[250:251], v[248:249], 0, s[98:99]
	global_load_dwordx4 v[232:235], v[250:251], off
	global_load_dwordx4 v[236:239], v[250:251], off offset:16
	global_load_dwordx4 v[240:243], v[250:251], off offset:512
	global_load_dwordx4 v[244:247], v[250:251], off offset:528
	s_waitcnt vmcnt(8)
	s_nop 1
	s_nop 1
	v_pk_add_f32 v[122:123], v[122:123], v[206:207]
	v_pk_add_f32 v[126:127], v[126:127], v[202:203]
	v_pk_add_f32 v[124:125], v[124:125], v[200:201]
	v_lshl_add_u64 v[152:153], s[12:13], 0, v[156:157]
	v_pk_add_f32 v[120:121], v[120:121], v[204:205]
	global_store_dwordx4 v[152:153], v[124:127], off
	global_store_dwordx4 v[152:153], v[120:123], off offset:16
	v_cvt_pk_bf16_f32 v148, v124, v125
	v_mul_f32_e32 v125, v125, v125
	v_fmac_f32_e32 v125, v124, v124
	v_mul_f32_e32 v124, v127, v127
	v_cvt_pk_bf16_f32 v150, v120, v121
	v_fmac_f32_e32 v124, v126, v126
	v_mul_f32_e32 v121, v121, v121
	v_add_f32_e32 v124, v125, v124
	v_fmac_f32_e32 v121, v120, v120
	v_cvt_pk_bf16_f32 v149, v126, v127
	v_cvt_pk_bf16_f32 v151, v122, v123
	v_lshl_add_u64 v[154:155], v[138:139], 1, s[18:19]
	v_add_f32_e32 v120, v124, v121
	v_mul_f32_e32 v121, v123, v123
	global_store_dwordx4 v[154:155], v[148:151], off
	v_fmac_f32_e32 v121, v122, v122
	s_nop 0
	v_add_f32_e32 v148, v121, v120
	s_nop 1
	s_nop 1
	v_pk_add_f32 v[114:115], v[114:115], v[214:215]
	v_pk_add_f32 v[118:119], v[118:119], v[210:211]
	v_pk_add_f32 v[116:117], v[116:117], v[208:209]
	v_pk_add_f32 v[112:113], v[112:113], v[212:213]
	global_store_dwordx4 v[152:153], v[116:119], off offset:512
	global_store_dwordx4 v[152:153], v[112:115], off offset:528
	v_cvt_pk_bf16_f32 v123, v114, v115
	v_cvt_pk_bf16_f32 v120, v116, v117
	v_mul_f32_e32 v115, v115, v115
	v_fmac_f32_e32 v115, v114, v114
	v_mul_f32_e32 v114, v117, v117
	v_fmac_f32_e32 v114, v116, v116
	v_mul_f32_e32 v116, v119, v119
	v_cvt_pk_bf16_f32 v122, v112, v113
	v_fmac_f32_e32 v116, v118, v118
	v_mul_f32_e32 v113, v113, v113
	v_add_f32_e32 v114, v114, v116
	v_fmac_f32_e32 v113, v112, v112
	v_add_f32_e32 v112, v114, v113
	v_add_f32_e32 v112, v115, v112
	v_add_f32_e32 v112, v148, v112
	ds_bpermute_b32 v113, v180, v112
	v_cvt_pk_bf16_f32 v121, v118, v119
	global_store_dwordx4 v[154:155], v[120:123], off offset:256
	s_waitcnt lgkmcnt(0)
	v_add_f32_e32 v114, v112, v113
	ds_bpermute_b32 v115, v181, v114
	v_lshl_add_u64 v[112:113], v[142:143], 3, s[14:15]
	s_and_saveexec_b64 s[28:29], s[8:9]
	s_cbranch_execz .LBB0_571
	s_waitcnt lgkmcnt(0)
	v_add_f32_e32 v114, v114, v115
	v_fma_f32 v114, v114, s65, 0.5
	v_trunc_f32_e32 v114, v114
	v_mul_f32_e32 v115, 0x2f800000, v114
	v_floor_f32_e32 v115, v115
	v_fmac_f32_e32 v114, 0xcf800000, v115
	v_cvt_u32_f32_e32 v114, v114
	v_cvt_u32_f32_e32 v115, v115
	global_atomic_add_x2 v[252:253], v[112:113], v[114:115], off sc0
.LBB0_571:
	s_or_b64 exec, exec, s[28:29]
	v_or_b32_e32 v114, 16, v142
	s_waitcnt lgkmcnt(0)
	v_ashrrev_i32_e32 v115, 31, v114
	v_lshlrev_b64 v[114:115], 10, v[114:115]
	v_lshl_add_u64 v[122:123], v[114:115], 0, v[140:141]
	v_lshlrev_b64 v[124:125], 2, v[122:123]
	v_lshl_add_u64 v[126:127], s[16:17], 0, v[124:125]
	s_mov_b64 s[98:99], 0x30000
	v_lshl_add_u64 v[250:251], v[248:249], 0, s[98:99]
	global_load_dwordx4 v[200:203], v[250:251], off
	global_load_dwordx4 v[204:207], v[250:251], off offset:16
	global_load_dwordx4 v[208:211], v[250:251], off offset:512
	global_load_dwordx4 v[212:215], v[250:251], off offset:528
	s_waitcnt vmcnt(12)
	s_nop 1
	s_nop 1
	v_lshl_add_u64 v[122:123], v[122:123], 1, s[18:19]
	v_lshl_add_u64 v[124:125], s[12:13], 0, v[124:125]
	v_pk_add_f32 v[110:111], v[110:111], v[218:219]
	v_pk_add_f32 v[108:109], v[108:109], v[216:217]
	v_pk_add_f32 v[106:107], v[106:107], v[222:223]
	v_pk_add_f32 v[104:105], v[104:105], v[220:221]
	v_cvt_pk_bf16_f32 v114, v108, v109
	v_cvt_pk_bf16_f32 v115, v110, v111
	v_cvt_pk_bf16_f32 v116, v104, v105
	v_cvt_pk_bf16_f32 v117, v106, v107
	global_store_dwordx4 v[124:125], v[108:111], off
	global_store_dwordx4 v[124:125], v[104:107], off offset:16
	global_store_dwordx4 v[122:123], v[114:117], off
	s_nop 1
	s_nop 0
	s_nop 1
	v_mul_f32_e32 v109, v109, v109
	v_mul_f32_e32 v111, v111, v111
	v_mul_f32_e32 v105, v105, v105
	v_fmac_f32_e32 v109, v108, v108
	v_fmac_f32_e32 v111, v110, v110
	v_mul_f32_e32 v107, v107, v107
	v_fmac_f32_e32 v105, v104, v104
	v_add_f32_e32 v104, v109, v111
	v_fmac_f32_e32 v107, v106, v106
	v_add_f32_e32 v104, v104, v105
	v_add_f32_e32 v108, v107, v104
	v_pk_add_f32 v[102:103], v[102:103], v[226:227]
	v_pk_add_f32 v[100:101], v[100:101], v[224:225]
	v_pk_add_f32 v[106:107], v[98:99], v[230:231]
	v_pk_add_f32 v[104:105], v[96:97], v[228:229]
	v_mul_f32_e32 v97, v101, v101
	v_mul_f32_e32 v98, v103, v103
	v_mul_f32_e32 v99, v105, v105
	v_fmac_f32_e32 v97, v100, v100
	v_fmac_f32_e32 v98, v102, v102
	v_mul_f32_e32 v96, v107, v107
	v_add_f32_e32 v97, v97, v98
	v_fmac_f32_e32 v99, v104, v104
	v_fmac_f32_e32 v96, v106, v106
	v_add_f32_e32 v97, v97, v99
	v_add_f32_e32 v96, v96, v97
	v_add_f32_e32 v96, v108, v96
	ds_bpermute_b32 v97, v180, v96
	global_store_dwordx4 v[124:125], v[100:103], off offset:512
	global_store_dwordx4 v[124:125], v[104:107], off offset:528
	v_cvt_pk_bf16_f32 v98, v100, v101
	v_cvt_pk_bf16_f32 v99, v102, v103
	v_cvt_pk_bf16_f32 v100, v104, v105
	s_waitcnt lgkmcnt(0)
	v_add_f32_e32 v96, v96, v97
	ds_bpermute_b32 v97, v181, v96
	v_cvt_pk_bf16_f32 v101, v106, v107
	global_store_dwordx4 v[122:123], v[98:101], off offset:256
	s_and_saveexec_b64 s[28:29], s[8:9]
	v_readlane_b32 s62, v254, 61
	v_readlane_b32 s66, v254, 63
	v_readlane_b32 s38, v254, 59
	v_readlane_b32 s63, v254, 62
	v_readlane_b32 s67, v255, 0
	v_readlane_b32 s39, v254, 60
	s_cbranch_execz .LBB0_573
	s_waitcnt lgkmcnt(0)
	v_add_f32_e32 v96, v96, v97
	v_fma_f32 v96, v96, s65, 0.5
	v_trunc_f32_e32 v96, v96
	v_mul_f32_e32 v97, 0x2f800000, v96
	v_floor_f32_e32 v97, v97
	v_fmac_f32_e32 v96, 0xcf800000, v97
	v_cvt_u32_f32_e32 v96, v96
	v_cvt_u32_f32_e32 v97, v97
	global_atomic_add_x2 v[252:253], v[112:113], v[96:97], off offset:128 sc0
.LBB0_573:
	s_or_b64 exec, exec, s[28:29]
	v_or_b32_e32 v96, 32, v142
	s_waitcnt lgkmcnt(0)
	v_ashrrev_i32_e32 v97, 31, v96
	v_lshlrev_b64 v[96:97], 10, v[96:97]
	v_lshl_add_u64 v[104:105], v[96:97], 0, v[140:141]
	v_lshlrev_b64 v[106:107], 2, v[104:105]
	v_lshl_add_u64 v[108:109], s[16:17], 0, v[106:107]
	s_mov_b64 s[98:99], 0x80000
	v_lshl_add_u64 v[250:251], v[248:249], 0, s[98:99]
	global_load_dwordx4 v[216:219], v[250:251], off
	global_load_dwordx4 v[220:223], v[250:251], off offset:16
	global_load_dwordx4 v[224:227], v[250:251], off offset:512
	global_load_dwordx4 v[228:231], v[250:251], off offset:528
	s_waitcnt vmcnt(16)
	s_nop 1
	s_nop 1
	v_lshl_add_u64 v[104:105], v[104:105], 1, s[18:19]
	v_lshl_add_u64 v[106:107], s[12:13], 0, v[106:107]
	v_pk_add_f32 v[94:95], v[94:95], v[234:235]
	v_pk_add_f32 v[92:93], v[92:93], v[232:233]
	v_pk_add_f32 v[90:91], v[90:91], v[238:239]
	v_pk_add_f32 v[88:89], v[88:89], v[236:237]
	v_cvt_pk_bf16_f32 v96, v92, v93
	v_cvt_pk_bf16_f32 v97, v94, v95
	v_cvt_pk_bf16_f32 v98, v88, v89
	v_cvt_pk_bf16_f32 v99, v90, v91
	global_store_dwordx4 v[106:107], v[92:95], off
	global_store_dwordx4 v[106:107], v[88:91], off offset:16
	global_store_dwordx4 v[104:105], v[96:99], off
	s_nop 1
	s_nop 0
	s_nop 1
	v_mul_f32_e32 v93, v93, v93
	v_mul_f32_e32 v95, v95, v95
	v_mul_f32_e32 v89, v89, v89
	v_fmac_f32_e32 v93, v92, v92
	v_fmac_f32_e32 v95, v94, v94
	v_mul_f32_e32 v91, v91, v91
	v_fmac_f32_e32 v89, v88, v88
	v_add_f32_e32 v88, v93, v95
	v_fmac_f32_e32 v91, v90, v90
	v_add_f32_e32 v88, v88, v89
	v_add_f32_e32 v92, v91, v88
	v_pk_add_f32 v[86:87], v[86:87], v[242:243]
	v_pk_add_f32 v[84:85], v[84:85], v[240:241]
	v_pk_add_f32 v[90:91], v[82:83], v[246:247]
	v_pk_add_f32 v[88:89], v[80:81], v[244:245]
	v_mul_f32_e32 v81, v85, v85
	v_mul_f32_e32 v82, v87, v87
	v_mul_f32_e32 v83, v89, v89
	v_fmac_f32_e32 v81, v84, v84
	v_fmac_f32_e32 v82, v86, v86
	v_mul_f32_e32 v80, v91, v91
	v_add_f32_e32 v81, v81, v82
	v_fmac_f32_e32 v83, v88, v88
	v_fmac_f32_e32 v80, v90, v90
	v_add_f32_e32 v81, v81, v83
	v_add_f32_e32 v80, v80, v81
	v_add_f32_e32 v80, v92, v80
	ds_bpermute_b32 v81, v180, v80
	global_store_dwordx4 v[106:107], v[84:87], off offset:512
	global_store_dwordx4 v[106:107], v[88:91], off offset:528
	v_cvt_pk_bf16_f32 v82, v84, v85
	v_cvt_pk_bf16_f32 v83, v86, v87
	v_cvt_pk_bf16_f32 v84, v88, v89
	s_waitcnt lgkmcnt(0)
	v_add_f32_e32 v80, v80, v81
	ds_bpermute_b32 v81, v181, v80
	v_cvt_pk_bf16_f32 v85, v90, v91
	global_store_dwordx4 v[104:105], v[82:85], off offset:256
	s_and_saveexec_b64 s[28:29], s[8:9]
	s_cbranch_execz .LBB0_575
	s_waitcnt lgkmcnt(0)
	v_add_f32_e32 v80, v80, v81
	v_fma_f32 v80, v80, s65, 0.5
	v_trunc_f32_e32 v80, v80
	v_mul_f32_e32 v81, 0x2f800000, v80
	v_floor_f32_e32 v81, v81
	v_fmac_f32_e32 v80, 0xcf800000, v81
	v_cvt_u32_f32_e32 v80, v80
	v_cvt_u32_f32_e32 v81, v81
	global_atomic_add_x2 v[252:253], v[112:113], v[80:81], off offset:256 sc0
.LBB0_575:
	s_or_b64 exec, exec, s[28:29]
	v_or_b32_e32 v80, 48, v142
	s_waitcnt lgkmcnt(0)
	v_ashrrev_i32_e32 v81, 31, v80
	v_lshlrev_b64 v[80:81], 10, v[80:81]
	v_lshl_add_u64 v[88:89], v[80:81], 0, v[140:141]
	v_lshlrev_b64 v[90:91], 2, v[88:89]
	v_lshl_add_u64 v[92:93], s[16:17], 0, v[90:91]
	s_mov_b64 s[98:99], 0x90000
	v_lshl_add_u64 v[250:251], v[248:249], 0, s[98:99]
	global_load_dwordx4 v[232:235], v[250:251], off
	global_load_dwordx4 v[236:239], v[250:251], off offset:16
	global_load_dwordx4 v[240:243], v[250:251], off offset:512
	global_load_dwordx4 v[244:247], v[250:251], off offset:528
	s_waitcnt vmcnt(16)
	s_nop 1
	s_nop 1
	v_lshl_add_u64 v[88:89], v[88:89], 1, s[18:19]
	v_lshl_add_u64 v[90:91], s[12:13], 0, v[90:91]
	v_pk_add_f32 v[78:79], v[78:79], v[202:203]
	v_pk_add_f32 v[76:77], v[76:77], v[200:201]
	v_pk_add_f32 v[74:75], v[74:75], v[206:207]
	v_pk_add_f32 v[72:73], v[72:73], v[204:205]
	v_cvt_pk_bf16_f32 v80, v76, v77
	v_cvt_pk_bf16_f32 v81, v78, v79
	v_cvt_pk_bf16_f32 v82, v72, v73
	v_cvt_pk_bf16_f32 v83, v74, v75
	global_store_dwordx4 v[90:91], v[76:79], off
	global_store_dwordx4 v[90:91], v[72:75], off offset:16
	global_store_dwordx4 v[88:89], v[80:83], off
	s_nop 1
	s_nop 0
	s_nop 1
	v_mul_f32_e32 v77, v77, v77
	v_mul_f32_e32 v79, v79, v79
	v_mul_f32_e32 v73, v73, v73
	v_fmac_f32_e32 v77, v76, v76
	v_fmac_f32_e32 v79, v78, v78
	v_mul_f32_e32 v75, v75, v75
	v_fmac_f32_e32 v73, v72, v72
	v_add_f32_e32 v72, v77, v79
	v_fmac_f32_e32 v75, v74, v74
	v_add_f32_e32 v72, v72, v73
	v_add_f32_e32 v76, v75, v72
	v_pk_add_f32 v[70:71], v[70:71], v[210:211]
	v_pk_add_f32 v[68:69], v[68:69], v[208:209]
	v_pk_add_f32 v[74:75], v[66:67], v[214:215]
	v_pk_add_f32 v[72:73], v[64:65], v[212:213]
	v_mul_f32_e32 v65, v69, v69
	v_mul_f32_e32 v66, v71, v71
	v_mul_f32_e32 v67, v73, v73
	v_fmac_f32_e32 v65, v68, v68
	v_fmac_f32_e32 v66, v70, v70
	v_mul_f32_e32 v64, v75, v75
	v_add_f32_e32 v65, v65, v66
	v_fmac_f32_e32 v67, v72, v72
	v_fmac_f32_e32 v64, v74, v74
	v_add_f32_e32 v65, v65, v67
	v_add_f32_e32 v64, v64, v65
	v_add_f32_e32 v64, v76, v64
	ds_bpermute_b32 v65, v180, v64
	global_store_dwordx4 v[90:91], v[68:71], off offset:512
	global_store_dwordx4 v[90:91], v[72:75], off offset:528
	v_cvt_pk_bf16_f32 v66, v68, v69
	v_cvt_pk_bf16_f32 v67, v70, v71
	v_cvt_pk_bf16_f32 v68, v72, v73
	s_waitcnt lgkmcnt(0)
	v_add_f32_e32 v64, v64, v65
	ds_bpermute_b32 v65, v181, v64
	v_cvt_pk_bf16_f32 v69, v74, v75
	global_store_dwordx4 v[88:89], v[66:69], off offset:256
	s_and_saveexec_b64 s[28:29], s[8:9]
	s_cbranch_execz .LBB0_577
	s_waitcnt lgkmcnt(0)
	v_add_f32_e32 v64, v64, v65
	v_fma_f32 v64, v64, s65, 0.5
	v_trunc_f32_e32 v64, v64
	v_mul_f32_e32 v65, 0x2f800000, v64
	v_floor_f32_e32 v65, v65
	v_fmac_f32_e32 v64, 0xcf800000, v65
	v_cvt_u32_f32_e32 v64, v64
	v_cvt_u32_f32_e32 v65, v65
	global_atomic_add_x2 v[252:253], v[112:113], v[64:65], off offset:384 sc0
.LBB0_577:
	s_or_b64 exec, exec, s[28:29]
	s_mov_b64 s[28:29], 0x20000
	v_lshl_add_u64 v[72:73], v[138:139], 0, s[28:29]
	v_lshlrev_b64 v[74:75], 2, v[72:73]
	v_lshl_add_u64 v[76:77], s[16:17], 0, v[74:75]
	s_waitcnt lgkmcnt(0)
	s_mov_b64 s[98:99], 0xa0000
	v_lshl_add_u64 v[250:251], v[248:249], 0, s[98:99]
	global_load_dwordx4 v[200:203], v[250:251], off
	global_load_dwordx4 v[204:207], v[250:251], off offset:16
	global_load_dwordx4 v[208:211], v[250:251], off offset:512
	global_load_dwordx4 v[212:215], v[250:251], off offset:528
	s_waitcnt vmcnt(16)
	s_nop 1
	s_nop 1
	v_lshl_add_u64 v[72:73], v[72:73], 1, s[18:19]
	v_lshl_add_u64 v[74:75], s[12:13], 0, v[74:75]
	v_pk_add_f32 v[62:63], v[62:63], v[218:219]
	v_pk_add_f32 v[60:61], v[60:61], v[216:217]
	v_pk_add_f32 v[58:59], v[58:59], v[222:223]
	v_pk_add_f32 v[56:57], v[56:57], v[220:221]
	v_cvt_pk_bf16_f32 v64, v60, v61
	v_cvt_pk_bf16_f32 v65, v62, v63
	v_cvt_pk_bf16_f32 v66, v56, v57
	v_cvt_pk_bf16_f32 v67, v58, v59
	global_store_dwordx4 v[74:75], v[60:63], off
	global_store_dwordx4 v[74:75], v[56:59], off offset:16
	global_store_dwordx4 v[72:73], v[64:67], off
	s_nop 1
	s_nop 0
	s_nop 1
	v_mul_f32_e32 v61, v61, v61
	v_mul_f32_e32 v63, v63, v63
	v_mul_f32_e32 v57, v57, v57
	v_fmac_f32_e32 v61, v60, v60
	v_fmac_f32_e32 v63, v62, v62
	v_mul_f32_e32 v59, v59, v59
	v_fmac_f32_e32 v57, v56, v56
	v_add_f32_e32 v56, v61, v63
	v_fmac_f32_e32 v59, v58, v58
	v_add_f32_e32 v56, v56, v57
	v_add_f32_e32 v60, v59, v56
	v_pk_add_f32 v[54:55], v[54:55], v[226:227]
	v_pk_add_f32 v[52:53], v[52:53], v[224:225]
	v_pk_add_f32 v[58:59], v[50:51], v[230:231]
	v_pk_add_f32 v[56:57], v[48:49], v[228:229]
	v_mul_f32_e32 v49, v53, v53
	v_mul_f32_e32 v50, v55, v55
	v_mul_f32_e32 v51, v57, v57
	v_fmac_f32_e32 v49, v52, v52
	v_fmac_f32_e32 v50, v54, v54
	v_mul_f32_e32 v48, v59, v59
	v_add_f32_e32 v49, v49, v50
	v_fmac_f32_e32 v51, v56, v56
	v_fmac_f32_e32 v48, v58, v58
	v_add_f32_e32 v49, v49, v51
	v_add_f32_e32 v48, v48, v49
	v_add_f32_e32 v48, v60, v48
	ds_bpermute_b32 v49, v180, v48
	global_store_dwordx4 v[74:75], v[52:55], off offset:512
	global_store_dwordx4 v[74:75], v[56:59], off offset:528
	v_cvt_pk_bf16_f32 v50, v52, v53
	v_cvt_pk_bf16_f32 v51, v54, v55
	v_cvt_pk_bf16_f32 v52, v56, v57
	s_waitcnt lgkmcnt(0)
	v_add_f32_e32 v48, v48, v49
	ds_bpermute_b32 v49, v181, v48
	v_cvt_pk_bf16_f32 v53, v58, v59
	global_store_dwordx4 v[72:73], v[50:53], off offset:256
	s_and_saveexec_b64 s[28:29], s[8:9]
	s_cbranch_execz .LBB0_579
	s_waitcnt lgkmcnt(0)
	v_add_f32_e32 v48, v48, v49
	v_fma_f32 v48, v48, s65, 0.5
	v_trunc_f32_e32 v48, v48
	v_mul_f32_e32 v49, 0x2f800000, v48
	v_floor_f32_e32 v49, v49
	v_fmac_f32_e32 v48, 0xcf800000, v49
	v_cvt_u32_f32_e32 v48, v48
	v_cvt_u32_f32_e32 v49, v49
	global_atomic_add_x2 v[252:253], v[112:113], v[48:49], off offset:1024 sc0
.LBB0_579:
	s_or_b64 exec, exec, s[28:29]
	s_mov_b64 s[28:29], 0x24000
	v_lshl_add_u64 v[56:57], v[138:139], 0, s[28:29]
	v_lshlrev_b64 v[58:59], 2, v[56:57]
	v_lshl_add_u64 v[60:61], s[16:17], 0, v[58:59]
	s_waitcnt lgkmcnt(0)
	s_mov_b64 s[98:99], 0xb0000
	v_lshl_add_u64 v[250:251], v[248:249], 0, s[98:99]
	global_load_dwordx4 v[216:219], v[250:251], off
	global_load_dwordx4 v[220:223], v[250:251], off offset:16
	global_load_dwordx4 v[224:227], v[250:251], off offset:512
	global_load_dwordx4 v[228:231], v[250:251], off offset:528
	s_waitcnt vmcnt(16)
	s_nop 1
	s_nop 1
	v_lshl_add_u64 v[56:57], v[56:57], 1, s[18:19]
	v_lshl_add_u64 v[58:59], s[12:13], 0, v[58:59]
	v_pk_add_f32 v[46:47], v[46:47], v[234:235]
	v_pk_add_f32 v[44:45], v[44:45], v[232:233]
	v_pk_add_f32 v[42:43], v[42:43], v[238:239]
	v_pk_add_f32 v[40:41], v[40:41], v[236:237]
	v_cvt_pk_bf16_f32 v48, v44, v45
	v_cvt_pk_bf16_f32 v49, v46, v47
	v_cvt_pk_bf16_f32 v50, v40, v41
	v_cvt_pk_bf16_f32 v51, v42, v43
	global_store_dwordx4 v[58:59], v[44:47], off
	global_store_dwordx4 v[58:59], v[40:43], off offset:16
	global_store_dwordx4 v[56:57], v[48:51], off
	s_nop 1
	s_nop 0
	s_nop 1
	v_mul_f32_e32 v45, v45, v45
	v_mul_f32_e32 v47, v47, v47
	v_mul_f32_e32 v41, v41, v41
	v_fmac_f32_e32 v45, v44, v44
	v_fmac_f32_e32 v47, v46, v46
	v_mul_f32_e32 v43, v43, v43
	v_fmac_f32_e32 v41, v40, v40
	v_add_f32_e32 v40, v45, v47
	v_fmac_f32_e32 v43, v42, v42
	v_add_f32_e32 v40, v40, v41
	v_add_f32_e32 v44, v43, v40
	v_pk_add_f32 v[38:39], v[38:39], v[242:243]
	v_pk_add_f32 v[36:37], v[36:37], v[240:241]
	v_pk_add_f32 v[42:43], v[34:35], v[246:247]
	v_pk_add_f32 v[40:41], v[32:33], v[244:245]
	v_mul_f32_e32 v33, v37, v37
	v_mul_f32_e32 v34, v39, v39
	v_mul_f32_e32 v35, v41, v41
	v_fmac_f32_e32 v33, v36, v36
	v_fmac_f32_e32 v34, v38, v38
	v_mul_f32_e32 v32, v43, v43
	v_add_f32_e32 v33, v33, v34
	v_fmac_f32_e32 v35, v40, v40
	v_fmac_f32_e32 v32, v42, v42
	v_add_f32_e32 v33, v33, v35
	v_add_f32_e32 v32, v32, v33
	v_add_f32_e32 v32, v44, v32
	ds_bpermute_b32 v33, v180, v32
	global_store_dwordx4 v[58:59], v[36:39], off offset:512
	global_store_dwordx4 v[58:59], v[40:43], off offset:528
	v_cvt_pk_bf16_f32 v34, v36, v37
	v_cvt_pk_bf16_f32 v35, v38, v39
	v_cvt_pk_bf16_f32 v36, v40, v41
	s_waitcnt lgkmcnt(0)
	v_add_f32_e32 v32, v32, v33
	ds_bpermute_b32 v33, v181, v32
	v_cvt_pk_bf16_f32 v37, v42, v43
	global_store_dwordx4 v[56:57], v[34:37], off offset:256
	s_and_saveexec_b64 s[28:29], s[8:9]
	s_cbranch_execz .LBB0_581
	s_waitcnt lgkmcnt(0)
	v_add_f32_e32 v32, v32, v33
	v_fma_f32 v32, v32, s65, 0.5
	v_trunc_f32_e32 v32, v32
	v_mul_f32_e32 v33, 0x2f800000, v32
	v_floor_f32_e32 v33, v33
	v_fmac_f32_e32 v32, 0xcf800000, v33
	v_cvt_u32_f32_e32 v32, v32
	v_cvt_u32_f32_e32 v33, v33
	global_atomic_add_x2 v[252:253], v[112:113], v[32:33], off offset:1152 sc0
.LBB0_581:
	s_or_b64 exec, exec, s[28:29]
	s_mov_b64 s[28:29], 0x28000
	v_lshl_add_u64 v[40:41], v[138:139], 0, s[28:29]
	v_lshlrev_b64 v[42:43], 2, v[40:41]
	v_lshl_add_u64 v[44:45], s[16:17], 0, v[42:43]
	s_waitcnt lgkmcnt(0)
	s_waitcnt vmcnt(12)
	s_nop 1
	s_nop 1
	v_lshl_add_u64 v[40:41], v[40:41], 1, s[18:19]
	v_lshl_add_u64 v[42:43], s[12:13], 0, v[42:43]
	v_pk_add_f32 v[30:31], v[30:31], v[202:203]
	v_pk_add_f32 v[28:29], v[28:29], v[200:201]
	v_pk_add_f32 v[26:27], v[26:27], v[206:207]
	v_pk_add_f32 v[24:25], v[24:25], v[204:205]
	v_cvt_pk_bf16_f32 v32, v28, v29
	v_cvt_pk_bf16_f32 v33, v30, v31
	v_cvt_pk_bf16_f32 v34, v24, v25
	v_cvt_pk_bf16_f32 v35, v26, v27
	global_store_dwordx4 v[42:43], v[28:31], off
	global_store_dwordx4 v[42:43], v[24:27], off offset:16
	global_store_dwordx4 v[40:41], v[32:35], off
	s_nop 1
	s_nop 0
	s_nop 1
	v_mul_f32_e32 v29, v29, v29
	v_mul_f32_e32 v31, v31, v31
	v_mul_f32_e32 v25, v25, v25
	v_fmac_f32_e32 v29, v28, v28
	v_fmac_f32_e32 v31, v30, v30
	v_mul_f32_e32 v27, v27, v27
	v_fmac_f32_e32 v25, v24, v24
	v_add_f32_e32 v24, v29, v31
	v_fmac_f32_e32 v27, v26, v26
	v_add_f32_e32 v24, v24, v25
	v_add_f32_e32 v28, v27, v24
	v_pk_add_f32 v[22:23], v[22:23], v[210:211]
	v_pk_add_f32 v[20:21], v[20:21], v[208:209]
	v_pk_add_f32 v[26:27], v[18:19], v[214:215]
	v_pk_add_f32 v[24:25], v[16:17], v[212:213]
	v_mul_f32_e32 v17, v21, v21
	v_mul_f32_e32 v18, v23, v23
	v_mul_f32_e32 v19, v25, v25
	v_fmac_f32_e32 v17, v20, v20
	v_fmac_f32_e32 v18, v22, v22
	v_mul_f32_e32 v16, v27, v27
	v_add_f32_e32 v17, v17, v18
	v_fmac_f32_e32 v19, v24, v24
	v_fmac_f32_e32 v16, v26, v26
	v_add_f32_e32 v17, v17, v19
	v_add_f32_e32 v16, v16, v17
	v_add_f32_e32 v16, v28, v16
	ds_bpermute_b32 v17, v180, v16
	global_store_dwordx4 v[42:43], v[20:23], off offset:512
	global_store_dwordx4 v[42:43], v[24:27], off offset:528
	v_cvt_pk_bf16_f32 v18, v20, v21
	v_cvt_pk_bf16_f32 v19, v22, v23
	v_cvt_pk_bf16_f32 v20, v24, v25
	s_waitcnt lgkmcnt(0)
	v_add_f32_e32 v16, v16, v17
	ds_bpermute_b32 v17, v181, v16
	v_cvt_pk_bf16_f32 v21, v26, v27
	global_store_dwordx4 v[40:41], v[18:21], off offset:256
	s_and_saveexec_b64 s[28:29], s[8:9]
	s_cbranch_execz .LBB0_583
	s_waitcnt lgkmcnt(0)
	v_add_f32_e32 v16, v16, v17
	v_fma_f32 v16, v16, s65, 0.5
	v_trunc_f32_e32 v16, v16
	v_mul_f32_e32 v17, 0x2f800000, v16
	v_floor_f32_e32 v17, v17
	v_fmac_f32_e32 v16, 0xcf800000, v17
	v_cvt_u32_f32_e32 v16, v16
	v_cvt_u32_f32_e32 v17, v17
	global_atomic_add_x2 v[252:253], v[112:113], v[16:17], off offset:1280 sc0
.LBB0_583:
	s_or_b64 exec, exec, s[28:29]
	s_mov_b64 s[28:29], 0x2c000
	v_lshl_add_u64 v[24:25], v[138:139], 0, s[28:29]
	v_lshlrev_b64 v[26:27], 2, v[24:25]
	v_lshl_add_u64 v[28:29], s[16:17], 0, v[26:27]
	s_waitcnt lgkmcnt(0)
	s_waitcnt vmcnt(8)
	s_nop 1
	s_nop 1
	v_lshl_add_u64 v[24:25], v[24:25], 1, s[18:19]
	v_lshl_add_u64 v[26:27], s[12:13], 0, v[26:27]
	v_pk_add_f32 v[14:15], v[14:15], v[218:219]
	v_pk_add_f32 v[12:13], v[12:13], v[216:217]
	v_pk_add_f32 v[10:11], v[10:11], v[222:223]
	v_pk_add_f32 v[8:9], v[8:9], v[220:221]
	v_cvt_pk_bf16_f32 v16, v12, v13
	v_cvt_pk_bf16_f32 v17, v14, v15
	v_cvt_pk_bf16_f32 v18, v8, v9
	v_cvt_pk_bf16_f32 v19, v10, v11
	global_store_dwordx4 v[26:27], v[12:15], off
	global_store_dwordx4 v[26:27], v[8:11], off offset:16
	global_store_dwordx4 v[24:25], v[16:19], off
	s_nop 1
	s_nop 0
	s_nop 1
	v_mul_f32_e32 v13, v13, v13
	v_mul_f32_e32 v15, v15, v15
	v_mul_f32_e32 v9, v9, v9
	v_fmac_f32_e32 v13, v12, v12
	v_fmac_f32_e32 v15, v14, v14
	v_mul_f32_e32 v11, v11, v11
	v_fmac_f32_e32 v9, v8, v8
	v_add_f32_e32 v8, v13, v15
	v_fmac_f32_e32 v11, v10, v10
	v_add_f32_e32 v8, v8, v9
	v_add_f32_e32 v12, v11, v8
	v_pk_add_f32 v[6:7], v[6:7], v[226:227]
	v_pk_add_f32 v[4:5], v[4:5], v[224:225]
	v_pk_add_f32 v[10:11], v[2:3], v[230:231]
	v_pk_add_f32 v[8:9], v[0:1], v[228:229]
	v_mul_f32_e32 v1, v5, v5
	v_mul_f32_e32 v2, v7, v7
	v_mul_f32_e32 v3, v9, v9
	v_fmac_f32_e32 v1, v4, v4
	v_fmac_f32_e32 v2, v6, v6
	v_mul_f32_e32 v0, v11, v11
	v_add_f32_e32 v1, v1, v2
	v_fmac_f32_e32 v3, v8, v8
	v_fmac_f32_e32 v0, v10, v10
	v_add_f32_e32 v1, v1, v3
	v_add_f32_e32 v0, v0, v1
	v_add_f32_e32 v0, v12, v0
	ds_bpermute_b32 v1, v180, v0
	global_store_dwordx4 v[26:27], v[4:7], off offset:512
	global_store_dwordx4 v[26:27], v[8:11], off offset:528
	v_cvt_pk_bf16_f32 v2, v4, v5
	v_cvt_pk_bf16_f32 v3, v6, v7
	v_cvt_pk_bf16_f32 v4, v8, v9
	s_waitcnt lgkmcnt(0)
	v_add_f32_e32 v0, v0, v1
	ds_bpermute_b32 v1, v181, v0
	v_cvt_pk_bf16_f32 v5, v10, v11
	global_store_dwordx4 v[24:25], v[2:5], off offset:256
	s_and_saveexec_b64 s[28:29], s[8:9]
	s_cbranch_execz .LBB0_560
	s_waitcnt lgkmcnt(0)
	v_add_f32_e32 v0, v0, v1
	v_fma_f32 v0, v0, s65, 0.5
	v_trunc_f32_e32 v0, v0
	v_mul_f32_e32 v1, 0x2f800000, v0
	v_floor_f32_e32 v1, v1
	v_fmac_f32_e32 v0, 0xcf800000, v1
	v_cvt_u32_f32_e32 v0, v0
	v_cvt_u32_f32_e32 v1, v1
	global_atomic_add_x2 v[252:253], v[112:113], v[0:1], off offset:1408 sc0
	s_branch .LBB0_560
